# sample-row final pass spread over all workgroups (wave 0 of workgroup b handles row b)
# baseline (speedup 1.0000x reference)
.LBB0_797:
	s_or_b64 exec, exec, s[0:1]
	s_waitcnt lgkmcnt(0)
	s_barrier
	v_readlane_b32 s0, v252, 0
	v_ashrrev_i32_e32 v44, 6, v0
	v_and_b32_e32 v45, 63, v0
	v_add_u32_e32 v54, s0, v44
	s_nop 0
	v_readfirstlane_b32 s4, v44
	s_nop 3
	s_cmp_lg_u32 s4, 0
	s_cbranch_scc1 .Lsn_done
	s_lshr_b32 s4, s0, 3
	s_lshl_b32 s5, s4, 12
	s_add_u32 s6, s78, s5
	s_addc_u32 s7, s79, 0
	s_add_u32 s6, s6, 0x10000000
	s_addc_u32 s7, s7, 0
	s_add_u32 s8, s80, s5
	s_addc_u32 s9, s81, 0
	s_add_u32 s8, s8, 0x24d48800
	s_addc_u32 s9, s9, 0
	v_lshlrev_b32_e32 v16, 4, v45
	global_load_dwordx4 v[0:3], v16, s[6:7]
	global_load_dwordx4 v[4:7], v16, s[6:7] offset:1024
	global_load_dwordx4 v[8:11], v16, s[6:7] offset:2048
	global_load_dwordx4 v[12:15], v16, s[6:7] offset:3072
	global_load_dwordx4 v[20:23], v16, s[76:77]
	global_load_dwordx4 v[24:27], v16, s[76:77] offset:1024
	global_load_dwordx4 v[28:31], v16, s[76:77] offset:2048
	global_load_dwordx4 v[32:35], v16, s[76:77] offset:3072
	global_load_dwordx4 v[56:59], v16, s[8:9]
	global_load_dwordx4 v[60:63], v16, s[8:9] offset:1024
	global_load_dwordx4 v[64:67], v16, s[8:9] offset:2048
	global_load_dwordx4 v[68:71], v16, s[8:9] offset:3072
	s_add_u32 s8, s8, 0x100000
	s_addc_u32 s9, s9, 0
	global_load_dwordx4 v[72:75], v16, s[8:9]
	global_load_dwordx4 v[76:79], v16, s[8:9] offset:1024
	global_load_dwordx4 v[80:83], v16, s[8:9] offset:2048
	global_load_dwordx4 v[84:87], v16, s[8:9] offset:3072
	s_add_u32 s8, s8, 0x100000
	s_addc_u32 s9, s9, 0
	global_load_dwordx4 v[88:91], v16, s[8:9]
	global_load_dwordx4 v[92:95], v16, s[8:9] offset:1024
	global_load_dwordx4 v[96:99], v16, s[8:9] offset:2048
	global_load_dwordx4 v[100:103], v16, s[8:9] offset:3072
	s_add_u32 s8, s8, 0x100000
	s_addc_u32 s9, s9, 0
	global_load_dwordx4 v[104:107], v16, s[8:9]
	global_load_dwordx4 v[108:111], v16, s[8:9] offset:1024
	global_load_dwordx4 v[112:115], v16, s[8:9] offset:2048
	global_load_dwordx4 v[116:119], v16, s[8:9] offset:3072
	s_add_u32 s8, s8, 0x100000
	s_addc_u32 s9, s9, 0
	global_load_dwordx4 v[120:123], v16, s[8:9]
	global_load_dwordx4 v[124:127], v16, s[8:9] offset:1024
	global_load_dwordx4 v[128:131], v16, s[8:9] offset:2048
	global_load_dwordx4 v[132:135], v16, s[8:9] offset:3072
	s_add_u32 s8, s8, 0x100000
	s_addc_u32 s9, s9, 0
	global_load_dwordx4 v[136:139], v16, s[8:9]
	global_load_dwordx4 v[140:143], v16, s[8:9] offset:1024
	global_load_dwordx4 v[144:147], v16, s[8:9] offset:2048
	global_load_dwordx4 v[148:151], v16, s[8:9] offset:3072
	s_add_u32 s8, s8, 0x100000
	s_addc_u32 s9, s9, 0
	global_load_dwordx4 v[152:155], v16, s[8:9]
	global_load_dwordx4 v[156:159], v16, s[8:9] offset:1024
	global_load_dwordx4 v[160:163], v16, s[8:9] offset:2048
	global_load_dwordx4 v[164:167], v16, s[8:9] offset:3072
	s_add_u32 s8, s8, 0x100000
	s_addc_u32 s9, s9, 0
	global_load_dwordx4 v[168:171], v16, s[8:9]
	global_load_dwordx4 v[172:175], v16, s[8:9] offset:1024
	global_load_dwordx4 v[176:179], v16, s[8:9] offset:2048
	global_load_dwordx4 v[180:183], v16, s[8:9] offset:3072
	s_add_u32 s8, s8, 0x100000
	s_addc_u32 s9, s9, 0
	global_load_dwordx4 v[184:187], v16, s[8:9]
	global_load_dwordx4 v[188:191], v16, s[8:9] offset:1024
	global_load_dwordx4 v[192:195], v16, s[8:9] offset:2048
	global_load_dwordx4 v[196:199], v16, s[8:9] offset:3072
	s_add_u32 s8, s8, 0x100000
	s_addc_u32 s9, s9, 0
	global_load_dwordx4 v[200:203], v16, s[8:9]
	global_load_dwordx4 v[204:207], v16, s[8:9] offset:1024
	global_load_dwordx4 v[212:215], v16, s[8:9] offset:2048
	global_load_dwordx4 v[216:219], v16, s[8:9] offset:3072
	s_add_u32 s8, s8, 0x100000
	s_addc_u32 s9, s9, 0
	global_load_dwordx4 v[220:223], v16, s[8:9]
	global_load_dwordx4 v[224:227], v16, s[8:9] offset:1024
	global_load_dwordx4 v[228:231], v16, s[8:9] offset:2048
	global_load_dwordx4 v[232:235], v16, s[8:9] offset:3072
	v_xor_b32_e32 v40, 1, v45
	v_xor_b32_e32 v41, 2, v45
	v_xor_b32_e32 v42, 4, v45
	v_xor_b32_e32 v43, 8, v45
	v_xor_b32_e32 v46, 16, v45
	v_xor_b32_e32 v47, 32, v45
	v_lshlrev_b32_e32 v40, 2, v40
	v_lshlrev_b32_e32 v41, 2, v41
	v_lshlrev_b32_e32 v42, 2, v42
	v_lshlrev_b32_e32 v43, 2, v43
	v_lshlrev_b32_e32 v46, 2, v46
	v_lshlrev_b32_e32 v47, 2, v47
	s_waitcnt vmcnt(0)
	v_pk_add_f32 v[0:1], v[0:1], v[56:57]
	v_pk_add_f32 v[2:3], v[2:3], v[58:59]
	v_pk_add_f32 v[4:5], v[4:5], v[60:61]
	v_pk_add_f32 v[6:7], v[6:7], v[62:63]
	v_pk_add_f32 v[8:9], v[8:9], v[64:65]
	v_pk_add_f32 v[10:11], v[10:11], v[66:67]
	v_pk_add_f32 v[12:13], v[12:13], v[68:69]
	v_pk_add_f32 v[14:15], v[14:15], v[70:71]
	v_pk_add_f32 v[0:1], v[0:1], v[72:73]
	v_pk_add_f32 v[2:3], v[2:3], v[74:75]
	v_pk_add_f32 v[4:5], v[4:5], v[76:77]
	v_pk_add_f32 v[6:7], v[6:7], v[78:79]
	v_pk_add_f32 v[8:9], v[8:9], v[80:81]
	v_pk_add_f32 v[10:11], v[10:11], v[82:83]
	v_pk_add_f32 v[12:13], v[12:13], v[84:85]
	v_pk_add_f32 v[14:15], v[14:15], v[86:87]
	v_pk_add_f32 v[0:1], v[0:1], v[88:89]
	v_pk_add_f32 v[2:3], v[2:3], v[90:91]
	v_pk_add_f32 v[4:5], v[4:5], v[92:93]
	v_pk_add_f32 v[6:7], v[6:7], v[94:95]
	v_pk_add_f32 v[8:9], v[8:9], v[96:97]
	v_pk_add_f32 v[10:11], v[10:11], v[98:99]
	v_pk_add_f32 v[12:13], v[12:13], v[100:101]
	v_pk_add_f32 v[14:15], v[14:15], v[102:103]
	v_pk_add_f32 v[0:1], v[0:1], v[104:105]
	v_pk_add_f32 v[2:3], v[2:3], v[106:107]
	v_pk_add_f32 v[4:5], v[4:5], v[108:109]
	v_pk_add_f32 v[6:7], v[6:7], v[110:111]
	v_pk_add_f32 v[8:9], v[8:9], v[112:113]
	v_pk_add_f32 v[10:11], v[10:11], v[114:115]
	v_pk_add_f32 v[12:13], v[12:13], v[116:117]
	v_pk_add_f32 v[14:15], v[14:15], v[118:119]
	v_pk_add_f32 v[0:1], v[0:1], v[120:121]
	v_pk_add_f32 v[2:3], v[2:3], v[122:123]
	v_pk_add_f32 v[4:5], v[4:5], v[124:125]
	v_pk_add_f32 v[6:7], v[6:7], v[126:127]
	v_pk_add_f32 v[8:9], v[8:9], v[128:129]
	v_pk_add_f32 v[10:11], v[10:11], v[130:131]
	v_pk_add_f32 v[12:13], v[12:13], v[132:133]
	v_pk_add_f32 v[14:15], v[14:15], v[134:135]
	v_pk_add_f32 v[0:1], v[0:1], v[136:137]
	v_pk_add_f32 v[2:3], v[2:3], v[138:139]
	v_pk_add_f32 v[4:5], v[4:5], v[140:141]
	v_pk_add_f32 v[6:7], v[6:7], v[142:143]
	v_pk_add_f32 v[8:9], v[8:9], v[144:145]
	v_pk_add_f32 v[10:11], v[10:11], v[146:147]
	v_pk_add_f32 v[12:13], v[12:13], v[148:149]
	v_pk_add_f32 v[14:15], v[14:15], v[150:151]
	v_pk_add_f32 v[0:1], v[0:1], v[152:153]
	v_pk_add_f32 v[2:3], v[2:3], v[154:155]
	v_pk_add_f32 v[4:5], v[4:5], v[156:157]
	v_pk_add_f32 v[6:7], v[6:7], v[158:159]
	v_pk_add_f32 v[8:9], v[8:9], v[160:161]
	v_pk_add_f32 v[10:11], v[10:11], v[162:163]
	v_pk_add_f32 v[12:13], v[12:13], v[164:165]
	v_pk_add_f32 v[14:15], v[14:15], v[166:167]
	v_pk_add_f32 v[0:1], v[0:1], v[168:169]
	v_pk_add_f32 v[2:3], v[2:3], v[170:171]
	v_pk_add_f32 v[4:5], v[4:5], v[172:173]
	v_pk_add_f32 v[6:7], v[6:7], v[174:175]
	v_pk_add_f32 v[8:9], v[8:9], v[176:177]
	v_pk_add_f32 v[10:11], v[10:11], v[178:179]
	v_pk_add_f32 v[12:13], v[12:13], v[180:181]
	v_pk_add_f32 v[14:15], v[14:15], v[182:183]
	v_pk_add_f32 v[0:1], v[0:1], v[184:185]
	v_pk_add_f32 v[2:3], v[2:3], v[186:187]
	v_pk_add_f32 v[4:5], v[4:5], v[188:189]
	v_pk_add_f32 v[6:7], v[6:7], v[190:191]
	v_pk_add_f32 v[8:9], v[8:9], v[192:193]
	v_pk_add_f32 v[10:11], v[10:11], v[194:195]
	v_pk_add_f32 v[12:13], v[12:13], v[196:197]
	v_pk_add_f32 v[14:15], v[14:15], v[198:199]
	v_pk_add_f32 v[0:1], v[0:1], v[200:201]
	v_pk_add_f32 v[2:3], v[2:3], v[202:203]
	v_pk_add_f32 v[4:5], v[4:5], v[204:205]
	v_pk_add_f32 v[6:7], v[6:7], v[206:207]
	v_pk_add_f32 v[8:9], v[8:9], v[212:213]
	v_pk_add_f32 v[10:11], v[10:11], v[214:215]
	v_pk_add_f32 v[12:13], v[12:13], v[216:217]
	v_pk_add_f32 v[14:15], v[14:15], v[218:219]
	v_pk_add_f32 v[0:1], v[0:1], v[220:221]
	v_pk_add_f32 v[2:3], v[2:3], v[222:223]
	v_pk_add_f32 v[4:5], v[4:5], v[224:225]
	v_pk_add_f32 v[6:7], v[6:7], v[226:227]
	v_pk_add_f32 v[8:9], v[8:9], v[228:229]
	v_pk_add_f32 v[10:11], v[10:11], v[230:231]
	v_pk_add_f32 v[12:13], v[12:13], v[232:233]
	v_pk_add_f32 v[14:15], v[14:15], v[234:235]
	v_mul_f32_e32 v17, v0, v0
	v_fmac_f32_e32 v17, v1, v1
	v_fmac_f32_e32 v17, v2, v2
	v_fmac_f32_e32 v17, v3, v3
	v_fmac_f32_e32 v17, v4, v4
	v_fmac_f32_e32 v17, v5, v5
	v_fmac_f32_e32 v17, v6, v6
	v_fmac_f32_e32 v17, v7, v7
	v_fmac_f32_e32 v17, v8, v8
	v_fmac_f32_e32 v17, v9, v9
	v_fmac_f32_e32 v17, v10, v10
	v_fmac_f32_e32 v17, v11, v11
	v_fmac_f32_e32 v17, v12, v12
	v_fmac_f32_e32 v17, v13, v13
	v_fmac_f32_e32 v17, v14, v14
	v_fmac_f32_e32 v17, v15, v15
	ds_bpermute_b32 v18, v40, v17
	s_waitcnt lgkmcnt(0)
	v_add_f32_e32 v17, v17, v18
	ds_bpermute_b32 v18, v41, v17
	s_waitcnt lgkmcnt(0)
	v_add_f32_e32 v17, v17, v18
	ds_bpermute_b32 v18, v42, v17
	s_waitcnt lgkmcnt(0)
	v_add_f32_e32 v17, v17, v18
	ds_bpermute_b32 v18, v43, v17
	s_waitcnt lgkmcnt(0)
	v_add_f32_e32 v17, v17, v18
	ds_bpermute_b32 v18, v46, v17
	s_waitcnt lgkmcnt(0)
	v_add_f32_e32 v17, v17, v18
	ds_bpermute_b32 v18, v47, v17
	s_waitcnt lgkmcnt(0)
	v_add_f32_e32 v17, v17, v18
	v_mov_b32_e32 v18, 0x358637bd
	v_fmac_f32_e32 v18, 0x3a800000, v17
	v_rsq_f32_e32 v18, v18
	s_nop 0
	v_mul_f32_e32 v0, v0, v18
	v_mul_f32_e32 v1, v1, v18
	v_mul_f32_e32 v2, v2, v18
	v_mul_f32_e32 v3, v3, v18
	v_mul_f32_e32 v4, v4, v18
	v_mul_f32_e32 v5, v5, v18
	v_mul_f32_e32 v6, v6, v18
	v_mul_f32_e32 v7, v7, v18
	v_mul_f32_e32 v8, v8, v18
	v_mul_f32_e32 v9, v9, v18
	v_mul_f32_e32 v10, v10, v18
	v_mul_f32_e32 v11, v11, v18
	v_mul_f32_e32 v12, v12, v18
	v_mul_f32_e32 v13, v13, v18
	v_mul_f32_e32 v14, v14, v18
	v_mul_f32_e32 v15, v15, v18
	v_pk_mul_f32 v[0:1], v[0:1], v[20:21]
	v_pk_mul_f32 v[2:3], v[2:3], v[22:23]
	v_pk_mul_f32 v[4:5], v[4:5], v[24:25]
	v_pk_mul_f32 v[6:7], v[6:7], v[26:27]
	v_pk_mul_f32 v[8:9], v[8:9], v[28:29]
	v_pk_mul_f32 v[10:11], v[10:11], v[30:31]
	v_pk_mul_f32 v[12:13], v[12:13], v[32:33]
	v_pk_mul_f32 v[14:15], v[14:15], v[34:35]
	global_store_dwordx4 v16, v[0:3], s[6:7]
	global_store_dwordx4 v16, v[4:7], s[6:7] offset:1024
	global_store_dwordx4 v16, v[8:11], s[6:7] offset:2048
	global_store_dwordx4 v16, v[12:15], s[6:7] offset:3072
